# layer-0 second-FFN weight conversion moved from phase 0 (all CUs) to the idle sliding-window half of the grid in phase 7 (scan-bound phase)
# speedup vs baseline: 1.0083x; 1.0055x over previous
; #define LAS __attribute__((address_space(3)))
; __device__ __forceinline__ void conv_matrix(const float* W, int K, int N, const float* gain, bf16_t* WT, int Kd, int mode, int row_off, LAS float* scr, int lane, int gw, int NGW) {
;     const int nblk = N / 32, items = nblk * (K / 64);
;     for (int it = gw; it < items; it += NGW) {
;         const int kb = it / nblk, nb = it % nblk, k0 = 64 * kb, n0 = 32 * nb;
;         float wv[32];
; #pragma unroll
;         for (int i = 0; i < 32; ++i) wv[i] = W[(size_t)(k0 + 2 * i + (lane >> 5)) * N + n0 + (lane & 31)];
; __device__ __forceinline__ void conv_ffn(const LAS Params* PL, int L, int which  , LAS float* scr, int lane, int gw, int NGW) {
;     const float* nrm = PL->in[which ? I_F2N : I_F1N] + (size_t)L * DM;
;     const float* wg = PL->in[which ? I_F2G : I_F1G] + (size_t)L * DM * FF;
;     const float* wu = PL->in[which ? I_F2U : I_F1U] + (size_t)L * DM * FF;
;     const float* wd = PL->in[which ? I_F2D : I_F1D] + (size_t)L * FF * DM;
;     bf16_t* gu = (bf16_t*)(PL->ws + (which ? (L ? WS_WGUC : WS_WGUB) : WS_WGUA)); bf16_t* dn = (bf16_t*)(PL->ws + (which ? (L ? WS_WDC : WS_WDB) : WS_WDA));
;     conv_matrix(wg, DM, FF, nrm, gu, DM, 1, 0, scr, lane, gw, NGW);
.Lconv_entry:
	s_ashr_i32 s5, s22, 6
	s_lshl_b32 s4, s12, 3
	s_add_i32 s4, s5, s4
	s_lshl_b32 s5, s5, 14
	s_lshl_b32 s8, s10, 3
	s_add_i32 s5, s5, 0
	s_cmpk_gt_i32 s4, 0x15ff
	v_and_b32_e32 v1, 63, v54
	s_cbranch_scc1 .LBB0_101
	v_readlane_b32 s9, v254, 2
	s_waitcnt vmcnt(0) lgkmcnt(0)
	v_mov_b32_e32 v19, v0
	v_lshlrev_b32_e32 v11, 3, v1
	v_mov_b32_e32 v2, s9
	v_readlane_b32 s9, v254, 3
	v_lshrrev_b32_e32 v64, 3, v1
	v_lshrrev_b32_e32 v35, 5, v1
	v_mov_b32_e32 v3, s9
	v_readlane_b32 s9, v254, 4
	ds_read_b64 v[8:9], v2
	ds_read2_b64 v[2:5], v3 offset1:1
	v_mov_b32_e32 v6, s9
	v_readlane_b32 s9, v254, 5
	v_mov_b32_e32 v15, v0
	s_mov_b64 s[16:17], 0x1500000
	v_mov_b32_e32 v10, s9
	ds_read_b64 v[6:7], v6
	ds_read_b64 v[12:13], v10
	v_and_b32_e32 v10, 31, v54
	v_lshlrev_b32_e32 v18, 2, v10
	s_lshl_b32 s9, s4, 5
	s_lshl_b32 s22, s4, 6
	s_waitcnt lgkmcnt(0)
	v_lshl_add_u64 v[16:17], v[12:13], 0, v[18:19]
	v_and_b32_e32 v12, 56, v11
	v_mul_u32_u24_e32 v11, 0x84, v12
	v_lshlrev_b32_e32 v14, 1, v12
	v_lshlrev_b32_e32 v13, 2, v64
	v_lshl_add_u64 v[14:15], v[6:7], 0, v[14:15]
	v_add3_u32 v55, s5, v11, v13
	v_mul_u32_u24_e32 v11, 0x84, v35
	v_cmp_ne_u64_e64 s[40:41], 0, v[8:9]
	v_lshl_add_u64 v[14:15], v[14:15], 0, s[16:17]
	v_add3_u32 v56, s5, v18, v11
	v_or_b32_e32 v65, 8, v64
	v_or_b32_e32 v66, 16, v64
	v_or_b32_e32 v67, 24, v64
	s_lshl_b32 s12, s8, 5
	s_lshl_b32 s23, s8, 6
	s_mov_b32 s24, s22
	s_mov_b32 s25, s9
	s_mov_b32 s27, s4
	s_cmp_eq_u32 s58, 7
	s_cbranch_scc1 .Lskip_a1
	s_branch .LBB0_81
.Lskip_a1:
	v_add_u32_e32 v57, 0x400, v56
	v_add_u32_e32 v58, 0x800, v56
	v_add_u32_e32 v59, 0xc00, v56
	v_add_u32_e32 v60, 0x1000, v56
	v_add_u32_e32 v61, 0x1400, v56
	v_add_u32_e32 v62, 0x1800, v56
	v_add_u32_e32 v63, 0x1c00, v56
	s_branch .LBB0_85

; #define LAS __attribute__((address_space(3)))
; __device__ __forceinline__ void conv_matrix(const float* W, int K, int N, const float* gain, bf16_t* WT, int Kd, int mode, int row_off, LAS float* scr, int lane, int gw, int NGW) {
;     const int nblk = N / 32, items = nblk * (K / 64);
;     for (int it = gw; it < items; it += NGW) {
;         const int kb = it / nblk, nb = it % nblk, k0 = 64 * kb, n0 = 32 * nb;
;         float wv[32];
; #pragma unroll
;         for (int i = 0; i < 32; ++i) wv[i] = W[(size_t)(k0 + 2 * i + (lane >> 5)) * N + n0 + (lane & 31)];
; __device__ __forceinline__ void conv_ffn(const LAS Params* PL, int L, int which  , LAS float* scr, int lane, int gw, int NGW) {
;     ...
;     conv_matrix(wu, DM, FF, nrm, gu, DM, 2, 0, scr, lane, gw, NGW);
.LBB0_85:
	v_lshlrev_b32_e32 v10, 2, v10
	v_mov_b32_e32 v11, v0
	v_lshl_add_u64 v[2:3], v[2:3], 0, v[10:11]
	s_mov_b32 s24, s22
	s_mov_b32 s25, s9
	s_mov_b32 s27, s4
	s_cmp_eq_u32 s58, 7
	s_cbranch_scc1 .LBB0_89
	s_branch .LBB0_87

; #define LAS __attribute__((address_space(3)))
; __device__ __forceinline__ void conv_matrix(const float* W, int K, int N, const float* gain, bf16_t* WT, int Kd, int mode, int row_off, LAS float* scr, int lane, int gw, int NGW) {
;     const int nblk = N / 32, items = nblk * (K / 64);
;     for (int it = gw; it < items; it += NGW) {
;         const int kb = it / nblk, nb = it % nblk, k0 = 64 * kb, n0 = 32 * nb;
;         float wv[32];
; #pragma unroll
;         for (int i = 0; i < 32; ++i) wv[i] = W[(size_t)(k0 + 2 * i + (lane >> 5)) * N + n0 + (lane & 31)];
; __device__ __forceinline__ void conv_ffn(const LAS Params* PL, int L, int which  , LAS float* scr, int lane, int gw, int NGW) {
;     ...
;     conv_matrix(wd, FF, DM, nullptr, dn, FF, 0, 0, scr, lane, gw, NGW);
.LBB0_89:
	v_mov_b32_e32 v11, v0
	v_lshlrev_b32_e32 v12, 1, v12
	v_mov_b32_e32 v13, v0
	v_lshl_add_u64 v[2:3], v[4:5], 0, v[10:11]
	v_lshl_add_u64 v[4:5], v[6:7], 0, v[12:13]
	s_mov_b64 s[16:17], 0x4100000
	v_lshl_add_u64 v[4:5], v[4:5], 0, s[16:17]
	s_mul_i32 s16, s4, 0x2c000
	v_mov_b32_e32 v6, s16
	s_movk_i32 s16, 0x1600
	v_mad_u32_u24 v68, v64, s16, v6
	s_mul_i32 s24, s8, 0x2c000
	s_mov_b32 s25, s9
	v_mov_b32_e32 v6, v68
	s_mov_b32 s27, s4
	s_cmp_eq_u32 s58, 7
	s_cbranch_scc1 .Lskip_a3

; #define LAS __attribute__((address_space(3)))
; __device__ __forceinline__ void conv_matrix(const float* W, int K, int N, const float* gain, bf16_t* WT, int Kd, int mode, int row_off, LAS float* scr, int lane, int gw, int NGW) {
;     const int nblk = N / 32, items = nblk * (K / 64);
;     for (int it = gw; it < items; it += NGW) {
;         const int kb = it / nblk, nb = it % nblk, k0 = 64 * kb, n0 = 32 * nb;
;         float wv[32];
; #pragma unroll
;         for (int i = 0; i < 32; ++i) wv[i] = W[(size_t)(k0 + 2 * i + (lane >> 5)) * N + n0 + (lane & 31)];
; __device__ __forceinline__ void conv_ffn(const LAS Params* PL, int L, int which  , LAS float* scr, int lane, int gw, int NGW) {
;     const float* nrm = PL->in[which ? I_F2N : I_F1N] + (size_t)L * DM;
;     const float* wg = PL->in[which ? I_F2G : I_F1G] + (size_t)L * DM * FF;
;     const float* wu = PL->in[which ? I_F2U : I_F1U] + (size_t)L * DM * FF;
;     const float* wd = PL->in[which ? I_F2D : I_F1D] + (size_t)L * FF * DM;
;     bf16_t* gu = (bf16_t*)(PL->ws + (which ? (L ? WS_WGUC : WS_WGUB) : WS_WGUA)); bf16_t* dn = (bf16_t*)(PL->ws + (which ? (L ? WS_WDC : WS_WDB) : WS_WDA));
;     conv_matrix(wg, DM, FF, nrm, gu, DM, 1, 0, scr, lane, gw, NGW);
.Lskip_a3:
	v_readlane_b32 s16, v254, 6
	v_mov_b32_e32 v13, v0
	s_mov_b32 s25, s22
	v_mov_b32_e32 v2, s16
	v_readlane_b32 s16, v254, 7
	s_mov_b32 s27, s9
	s_mov_b32 s33, s4
	v_mov_b32_e32 v3, s16
	v_readlane_b32 s16, v254, 4
	ds_read_b128 v[6:9], v2
	ds_read_b128 v[2:5], v3
	v_mov_b32_e32 v11, s16
	ds_read_b64 v[14:15], v11
	v_mov_b32_e32 v11, v0
	s_waitcnt lgkmcnt(0)
	v_lshl_add_u64 v[16:17], v[8:9], 0, v[10:11]
	s_mov_b64 s[16:17], 0x5700000
	v_cmp_ne_u64_e64 s[40:41], 0, v[6:7]
	v_lshl_add_u64 v[8:9], v[14:15], 0, v[12:13]
	v_lshl_add_u64 v[8:9], v[8:9], 0, s[16:17]
	s_cmp_eq_u32 s58, 0
	s_cbranch_scc1 .LBB0_95
	s_branch .LBB0_93

; #define LAS __attribute__((address_space(3)))
; __device__ __forceinline__ void conv_matrix(const float* W, int K, int N, const float* gain, bf16_t* WT, int Kd, int mode, int row_off, LAS float* scr, int lane, int gw, int NGW) {
;     const int nblk = N / 32, items = nblk * (K / 64);
;     for (int it = gw; it < items; it += NGW) {
;         const int kb = it / nblk, nb = it % nblk, k0 = 64 * kb, n0 = 32 * nb;
;         float wv[32];
; #pragma unroll
;         for (int i = 0; i < 32; ++i) wv[i] = W[(size_t)(k0 + 2 * i + (lane >> 5)) * N + n0 + (lane & 31)];
; __device__ __forceinline__ void conv_ffn(const LAS Params* PL, int L, int which  , LAS float* scr, int lane, int gw, int NGW) {
;     ...
;     conv_matrix(wu, DM, FF, nrm, gu, DM, 2, 0, scr, lane, gw, NGW);
.LBB0_95:
	v_mov_b32_e32 v11, v0
	v_lshl_add_u64 v[2:3], v[2:3], 0, v[10:11]
	s_mov_b32 s25, s9
	s_mov_b32 s27, s4
	s_cmp_eq_u32 s58, 0
	s_cbranch_scc1 .LBB0_99
	s_branch .LBB0_97

; #define LAS __attribute__((address_space(3)))
; __device__ __forceinline__ void conv_matrix(const float* W, int K, int N, const float* gain, bf16_t* WT, int Kd, int mode, int row_off, LAS float* scr, int lane, int gw, int NGW) {
;     const int nblk = N / 32, items = nblk * (K / 64);
;     for (int it = gw; it < items; it += NGW) {
;         const int kb = it / nblk, nb = it % nblk, k0 = 64 * kb, n0 = 32 * nb;
;         float wv[32];
; #pragma unroll
;         for (int i = 0; i < 32; ++i) wv[i] = W[(size_t)(k0 + 2 * i + (lane >> 5)) * N + n0 + (lane & 31)];
; __device__ __forceinline__ void conv_ffn(const LAS Params* PL, int L, int which  , LAS float* scr, int lane, int gw, int NGW) {
;     ...
;     conv_matrix(wd, FF, DM, nullptr, dn, FF, 0, 0, scr, lane, gw, NGW);
.LBB0_99:
	v_mov_b32_e32 v11, v0
	v_mov_b32_e32 v13, v0
	v_lshl_add_u64 v[2:3], v[4:5], 0, v[10:11]
	v_lshl_add_u64 v[4:5], v[14:15], 0, v[12:13]
	s_mov_b64 s[16:17], 0x8300000
	v_lshl_add_u64 v[4:5], v[4:5], 0, s[16:17]
	s_mov_b32 s22, s4
	s_cmp_eq_u32 s58, 0
	s_cbranch_scc1 .Lskip_b3

; #define LAS __attribute__((address_space(3)))
; __device__ __forceinline__ void conv_matrix(const float* W, int K, int N, const float* gain, bf16_t* WT, int Kd, int mode, int row_off, LAS float* scr, int lane, int gw, int NGW) {
;     const int nblk = N / 32, items = nblk * (K / 64);
;     for (int it = gw; it < items; it += NGW) {
;         const int kb = it / nblk, nb = it % nblk, k0 = 64 * kb, n0 = 32 * nb;
;         float wv[32];
; #pragma unroll
;         for (int i = 0; i < 32; ++i) wv[i] = W[(size_t)(k0 + 2 * i + (lane >> 5)) * N + n0 + (lane & 31)];
; __global__ void __launch_bounds__(NTHREADS, 2) hybrid_fwd(Params P) {
;     ...
;             conv_matrix(PL->in[I_ABIN], DM, ABN, PL->in[I_MIXN], (bf16_t*)(ws + WS_WABIN), DM, 0, 0, scr, lane, gw, NGW);
.Lskip_b3:
.LBB0_101:
	s_cmp_eq_u32 s58, 7
	s_cbranch_scc1 .Lconv_return
	s_cmpk_gt_i32 s4, 0x131f
	s_cbranch_scc1 .LBB0_106
	v_readlane_b32 s9, v254, 8
	v_lshlrev_b32_e32 v6, 2, v54
	v_and_b32_e32 v6, 0x7c, v6
	s_waitcnt lgkmcnt(0)
	v_mov_b32_e32 v2, s9
	v_readlane_b32 s9, v254, 9
	v_mov_b32_e32 v7, v0
	v_add_u32_e32 v8, s5, v6
	v_mov_b32_e32 v4, s9
	ds_read_b64 v[2:3], v2
	ds_read_b64 v[4:5], v4
	v_lshrrev_b32_e32 v44, 3, v1
	v_lshrrev_b32_e32 v35, 5, v1
	v_lshlrev_b32_e32 v10, 2, v44
	s_mov_b64 s[16:17], 0x9900000
	s_waitcnt lgkmcnt(0)
	v_lshl_add_u64 v[4:5], v[4:5], 0, v[6:7]
	v_lshlrev_b32_e32 v6, 3, v1
	v_and_b32_e32 v6, 56, v6
	v_mul_u32_u24_e32 v9, 0x84, v6
	v_lshlrev_b32_e32 v6, 1, v6
	v_lshl_add_u64 v[6:7], s[0:1], 0, v[6:7]
	v_add3_u32 v45, s5, v9, v10
	v_mul_u32_u24_e32 v9, 0x84, v35
	v_cmp_ne_u64_e64 s[38:39], 0, v[2:3]
	v_lshl_add_u64 v[6:7], v[6:7], 0, s[16:17]
	s_lshl_b32 s9, s4, 5
	s_lshl_b32 s12, s8, 5
	v_add_u32_e32 v46, v8, v9
	s_mov_b32 s22, s4
	s_branch .LBB0_104

; #define LAS __attribute__((address_space(3)))
; __global__ void __launch_bounds__(NTHREADS, 2) hybrid_fwd(Params P) {
;     ...
;                 const int gw2 = (bx - nscan) * 8 + wave, NGW2 = (G - nscan) * 8;
;                 conv_ffn(PL, 1, 0, (LAS float*)(lds + wave * 16384), lane, gw2, NGW2);
;                 conv_ffn(PL, 1, 1, (LAS float*)(lds + wave * 16384), lane, gw2, NGW2);
.LBB0_734:
	v_mov_b32_e32 v54, v236
	s_lshr_b32 s10, s56, 1
	s_sub_i32 s12, s73, s10
	s_sub_i32 s10, s56, s10
	v_readfirstlane_b32 s22, v54
	s_branch .Lconv_entry
